# v25: v22 + last layer's final residual epilogue no longer stores the unused bf16 activation copy
# speedup vs baseline: 1.0117x; 1.0117x over previous
; #define PG8_LAS __attribute__((address_space(3)))
; __device__ __forceinline__ unsigned cvt_pk_bf16(float lo, float hi) { unsigned r; asm volatile("v_cvt_pk_bf16_f32 %0, %1, %2" : "=v"(r) : "v"(lo), "v"(hi)); return r; }
; __device__ __forceinline__ float bperm(float v, int srclane) { return __int_as_float(__builtin_amdgcn_ds_bpermute(srclane << 2, __float_as_int(v))); }
; __device__ __forceinline__ float bperm(float v, int srclane) { return __int_as_float(__builtin_amdgcn_ds_bpermute(srclane << 2, __float_as_int(v))); }
;     __device__ __forceinline__ void fused(f32x4 (&acc)[2][2][4][2], const Unit& u, int wr, int wc, int fr, int fq, PG8_LAS unsigned char* lds, int wid, int lane) const {
;         float scl = scale; asm volatile("" : "+v"(scl)); const int row0 = u.pm * BM + wr * 64 + fr, col0 = u.pn * BM + wc * 32 + 4 * fq;
;         PG8_LAS float* P = (PG8_LAS float*)lds;
; #pragma unroll
;         for (int ai = 0; ai < 2; ++ai) { f32x4 xv[4][2][2];
; #pragma unroll
;             for (int m = 0; m < 4; ++m)
; #pragma unroll
;                 for (int bj = 0; bj < 2; ++bj)
; #pragma unroll
;                     for (int n = 0; n < 2; ++n) xv[m][bj][n] = *(const f32x4*)(xin + (size_t)(row0 + ai * HALF + m * 16) * 1024 + col0 + bj * HALF + n * 16);
;             __builtin_amdgcn_sched_barrier(0);
; #pragma unroll
;             for (int m = 0; m < 4; ++m) { const int row = row0 + ai * HALF + m * 16; float q = 0.f;
; #pragma unroll
;                 for (int bj = 0; bj < 2; ++bj)
; #pragma unroll
;                     for (int n = 0; n < 2; ++n) { const size_t off = (size_t)row * 1024 + col0 + bj * HALF + n * 16;
;                         f32x4 v = xv[m][bj][n] + acc[ai][bj][m][n] * scl; *(f32x4*)(x + off) = v;
;                         u32x2 w; w.x = cvt_pk_bf16(v[0], v[1]); w.y = cvt_pk_bf16(v[2], v[3]); *(u32x2*)(xb + off) = w;
;                         q += (v[0] * v[0] + v[1] * v[1]) + (v[2] * v[2] + v[3] * v[3]); }
;                 q += bperm(q, (fr + 16 * fq) ^ 16); q += bperm(q, (fr + 16 * fq) ^ 32);
;                 if (fq == 0) P[(ai * HALF + wr * 64 + m * 16 + fr) * 4 + wc] = q; }
.LBB0_1525:
	s_lshl_b32 s2, s23, 5
	s_lshl_b32 s4, s63, 8
	s_lshl_b32 s3, s70, 8
	v_bfe_u32 v130, v136, 4, 2
	s_add_i32 s25, s25, s4
	s_or_b32 s2, s2, s3
	v_or_b32_e32 v182, s25, v138
	v_lshl_or_b32 v180, v130, 2, s2
	v_ashrrev_i32_e32 v181, 31, v180
	v_lshlrev_b32_e32 v130, 6, v130
	v_ashrrev_i32_e32 v183, 31, v182
	v_or_b32_e32 v210, 16, v182
	v_bitop3_b32 v213, v130, 64, v137 bitop3:0x36
	v_bitop3_b32 v212, v130, s93, v137 bitop3:0x36
	v_lshl_add_u64 v[184:185], v[180:181], 2, s[76:77]
	v_lshlrev_b64 v[130:131], 12, v[182:183]
	v_ashrrev_i32_e32 v211, 31, v210
	v_or_b32_e32 v192, 32, v182
	v_lshl_add_u64 v[222:223], v[184:185], 0, v[130:131]
	v_lshlrev_b64 v[130:131], 12, v[210:211]
	v_ashrrev_i32_e32 v193, 31, v192
	v_or_b32_e32 v188, 48, v182
	v_lshl_add_u64 v[194:195], v[184:185], 0, v[130:131]
	v_lshlrev_b64 v[130:131], 12, v[192:193]
	v_ashrrev_i32_e32 v189, 31, v188
	v_lshl_add_u64 v[190:191], v[184:185], 0, v[130:131]
	v_lshlrev_b64 v[130:131], 12, v[188:189]
	v_mov_b32_e32 v178, 0.5
	v_lshl_add_u64 v[186:187], v[184:185], 0, v[130:131]
	v_and_b32_e32 v64, 63, v136
	s_barrier
	global_load_dwordx4 v[214:217], v[222:223], off
	global_load_dwordx4 v[218:221], v[222:223], off offset:64
	global_load_dwordx4 v[242:245], v[222:223], off offset:512
	global_load_dwordx4 v[246:249], v[222:223], off offset:576
	global_load_dwordx4 v[174:177], v[194:195], off
	global_load_dwordx4 v[170:173], v[194:195], off offset:64
	global_load_dwordx4 v[166:169], v[194:195], off offset:512
	global_load_dwordx4 v[162:165], v[194:195], off offset:576
	global_load_dwordx4 v[158:161], v[190:191], off
	global_load_dwordx4 v[154:157], v[190:191], off offset:64
	global_load_dwordx4 v[150:153], v[190:191], off offset:512
	global_load_dwordx4 v[146:149], v[190:191], off offset:576
	global_load_dwordx4 v[142:145], v[186:187], off
	global_load_dwordx4 v[138:141], v[186:187], off offset:64
	global_load_dwordx4 v[134:137], v[186:187], off offset:512
	global_load_dwordx4 v[130:133], v[186:187], off offset:576
	s_lshl_b32 s2, s23, 2
	s_add_i32 s2, s2, 0
	v_cmp_gt_u32_e32 vcc, 16, v64
	v_lshlrev_b64 v[230:231], 10, v[182:183]
	s_waitcnt vmcnt(0)
	v_pk_fma_f32 v[128:129], v[128:129], v[178:179], v[216:217] op_sel_hi:[1,0,1]
	v_pk_fma_f32 v[126:127], v[126:127], v[178:179], v[214:215] op_sel_hi:[1,0,1]
	v_lshl_add_u64 v[230:231], v[230:231], 0, v[180:181]
	global_store_dwordx4 v[222:223], v[126:129], off
	v_cvt_pk_bf16_f32 v214, v126, v127
	v_lshlrev_b64 v[216:217], 1, v[230:231]
	v_lshl_add_u64 v[230:231], s[26:27], 0, v[216:217]
	v_mul_f32_e32 v127, v127, v127
	v_fmac_f32_e32 v127, v126, v126
	v_mul_f32_e32 v126, v129, v129
	v_fmac_f32_e32 v126, v128, v128
	v_pk_fma_f32 v[124:125], v[124:125], v[178:179], v[220:221] op_sel_hi:[1,0,1]
	v_pk_fma_f32 v[122:123], v[122:123], v[178:179], v[218:219] op_sel_hi:[1,0,1]
	v_cvt_pk_bf16_f32 v215, v128, v129
	v_readlane_b32 s38, v254, 58
	v_readlane_b32 s39, v254, 59
	s_nop 3
	s_not_b64 s[38:39], s[38:39]
	s_and_saveexec_b64 s[44:45], s[38:39]
	global_store_dwordx2 v[230:231], v[214:215], off
	s_mov_b64 exec, s[44:45]
	v_add_f32_e32 v183, v127, v126
	global_store_dwordx4 v[222:223], v[122:125], off offset:64
	v_cvt_pk_bf16_f32 v126, v122, v123
	v_or_b32_e32 v128, 32, v216
	v_mov_b32_e32 v129, v217
	v_mul_f32_e32 v123, v123, v123
	v_fmac_f32_e32 v123, v122, v122
	v_mul_f32_e32 v122, v125, v125
	v_fmac_f32_e32 v122, v124, v124
	v_lshl_add_u64 v[128:129], s[26:27], 0, v[128:129]
	v_add_f32_e32 v122, v123, v122
	v_pk_fma_f32 v[120:121], v[120:121], v[178:179], v[244:245] op_sel_hi:[1,0,1]
	v_pk_fma_f32 v[118:119], v[118:119], v[178:179], v[242:243] op_sel_hi:[1,0,1]
	v_cvt_pk_bf16_f32 v127, v124, v125
	s_and_saveexec_b64 s[44:45], s[38:39]
	global_store_dwordx2 v[128:129], v[126:127], off
	s_mov_b64 exec, s[44:45]
	v_add_f32_e32 v126, v183, v122
	global_store_dwordx4 v[222:223], v[118:121], off offset:512
	v_cvt_pk_bf16_f32 v122, v118, v119
	v_pk_fma_f32 v[116:117], v[116:117], v[178:179], v[248:249] op_sel_hi:[1,0,1]
	v_pk_fma_f32 v[114:115], v[114:115], v[178:179], v[246:247] op_sel_hi:[1,0,1]
	v_mul_f32_e32 v119, v119, v119
	v_fmac_f32_e32 v119, v118, v118
	v_mul_f32_e32 v118, v121, v121
	v_fmac_f32_e32 v118, v120, v120
	v_cvt_pk_bf16_f32 v123, v120, v121
	v_add_f32_e32 v118, v119, v118
	v_mul_f32_e32 v119, v115, v115
	v_mul_f32_e32 v120, v117, v117
	v_fmac_f32_e32 v119, v114, v114
	v_fmac_f32_e32 v120, v116, v116
	v_add_f32_e32 v118, v118, v126
	v_add_f32_e32 v119, v119, v120
	v_add_f32_e32 v120, v119, v118
	ds_bpermute_b32 v121, v213, v120
	v_or_b32_e32 v124, 0x100, v216
	v_mov_b32_e32 v125, v217
	v_lshl_add_u64 v[124:125], s[26:27], 0, v[124:125]
	s_and_saveexec_b64 s[44:45], s[38:39]
	global_store_dwordx2 v[124:125], v[122:123], off
	s_mov_b64 exec, s[44:45]
	global_store_dwordx4 v[222:223], v[114:117], off offset:576
	v_cvt_pk_bf16_f32 v118, v114, v115
	v_or_b32_e32 v216, 0x120, v216
	v_cvt_pk_bf16_f32 v119, v116, v117
	v_lshl_add_u32 v128, v179, 4, s2
	s_waitcnt lgkmcnt(0)
	v_add_f32_e32 v114, v120, v121
	ds_bpermute_b32 v115, v212, v114
	v_lshl_add_u64 v[116:117], s[26:27], 0, v[216:217]
	s_and_saveexec_b64 s[44:45], s[38:39]
	global_store_dwordx2 v[116:117], v[118:119], off
	s_mov_b64 exec, s[44:45]
	s_and_saveexec_b64 s[2:3], vcc
	s_cbranch_execz .LBB0_1527
	s_waitcnt lgkmcnt(0)
	v_add_f32_e32 v114, v114, v115
	ds_write_b32 v128, v114
; __device__ __forceinline__ unsigned cvt_pk_bf16(float lo, float hi) { unsigned r; asm volatile("v_cvt_pk_bf16_f32 %0, %1, %2" : "=v"(r) : "v"(lo), "v"(hi)); return r; }
; __device__ __forceinline__ float bperm(float v, int srclane) { return __int_as_float(__builtin_amdgcn_ds_bpermute(srclane << 2, __float_as_int(v))); }
; __device__ __forceinline__ float bperm(float v, int srclane) { return __int_as_float(__builtin_amdgcn_ds_bpermute(srclane << 2, __float_as_int(v))); }
;     __device__ __forceinline__ void fused(f32x4 (&acc)[2][2][4][2], const Unit& u, int wr, int wc, int fr, int fq, PG8_LAS unsigned char* lds, int wid, int lane) const {
;     ...
;         for (int ai = 0; ai < 2; ++ai) { f32x4 xv[4][2][2];
; #pragma unroll
;             for (int m = 0; m < 4; ++m)
; #pragma unroll
;                 for (int bj = 0; bj < 2; ++bj)
; #pragma unroll
;                     for (int n = 0; n < 2; ++n) xv[m][bj][n] = *(const f32x4*)(xin + (size_t)(row0 + ai * HALF + m * 16) * 1024 + col0 + bj * HALF + n * 16);
;             __builtin_amdgcn_sched_barrier(0);
; #pragma unroll
;             for (int m = 0; m < 4; ++m) { const int row = row0 + ai * HALF + m * 16; float q = 0.f;
; #pragma unroll
;                 for (int bj = 0; bj < 2; ++bj)
; #pragma unroll
;                     for (int n = 0; n < 2; ++n) { const size_t off = (size_t)row * 1024 + col0 + bj * HALF + n * 16;
;                         f32x4 v = xv[m][bj][n] + acc[ai][bj][m][n] * scl; *(f32x4*)(x + off) = v;
;                         u32x2 w; w.x = cvt_pk_bf16(v[0], v[1]); w.y = cvt_pk_bf16(v[2], v[3]); *(u32x2*)(xb + off) = w;
;                         q += (v[0] * v[0] + v[1] * v[1]) + (v[2] * v[2] + v[3] * v[3]); }
;                 q += bperm(q, (fr + 16 * fq) ^ 16); q += bperm(q, (fr + 16 * fq) ^ 32);
;                 if (fq == 0) P[(ai * HALF + wr * 64 + m * 16 + fr) * 4 + wc] = q; }
.LBB0_1527:
	s_or_b64 exec, exec, s[2:3]
	s_waitcnt lgkmcnt(0)
	v_lshlrev_b64 v[114:115], 10, v[210:211]
	v_mov_b32_e32 v179, v178
	v_lshl_add_u64 v[116:117], v[114:115], 0, v[180:181]
	v_mov_b32_e32 v114, v178
	v_mov_b32_e32 v115, v178
	v_pk_fma_f32 v[112:113], v[112:113], v[114:115], v[176:177]
	v_pk_fma_f32 v[110:111], v[110:111], v[178:179], v[174:175]
	global_store_dwordx4 v[194:195], v[110:113], off
	v_cvt_pk_bf16_f32 v118, v110, v111
	v_lshlrev_b64 v[116:117], 1, v[116:117]
	v_lshl_add_u64 v[120:121], s[26:27], 0, v[116:117]
	v_mul_f32_e32 v111, v111, v111
	v_fmac_f32_e32 v111, v110, v110
	v_mul_f32_e32 v110, v113, v113
	v_fmac_f32_e32 v110, v112, v112
	v_pk_fma_f32 v[108:109], v[108:109], v[114:115], v[172:173]
	v_pk_fma_f32 v[106:107], v[106:107], v[178:179], v[170:171]
	v_cvt_pk_bf16_f32 v119, v112, v113
	s_and_saveexec_b64 s[44:45], s[38:39]
	global_store_dwordx2 v[120:121], v[118:119], off
	s_mov_b64 exec, s[44:45]
	v_add_f32_e32 v118, v111, v110
	global_store_dwordx4 v[194:195], v[106:109], off offset:64
	v_cvt_pk_bf16_f32 v110, v106, v107
	v_or_b32_e32 v112, 32, v116
	v_mov_b32_e32 v113, v117
	v_mul_f32_e32 v107, v107, v107
	v_fmac_f32_e32 v107, v106, v106
	v_mul_f32_e32 v106, v109, v109
	v_fmac_f32_e32 v106, v108, v108
	v_lshl_add_u64 v[112:113], s[26:27], 0, v[112:113]
	v_add_f32_e32 v106, v107, v106
	v_pk_fma_f32 v[104:105], v[104:105], v[114:115], v[168:169]
	v_pk_fma_f32 v[102:103], v[102:103], v[178:179], v[166:167]
	v_cvt_pk_bf16_f32 v111, v108, v109
	s_and_saveexec_b64 s[44:45], s[38:39]
	global_store_dwordx2 v[112:113], v[110:111], off
	s_mov_b64 exec, s[44:45]
	v_add_f32_e32 v110, v118, v106
	global_store_dwordx4 v[194:195], v[102:105], off offset:512
	v_cvt_pk_bf16_f32 v106, v102, v103
	v_pk_fma_f32 v[100:101], v[100:101], v[114:115], v[164:165]
	v_pk_fma_f32 v[98:99], v[98:99], v[178:179], v[162:163]
	v_mul_f32_e32 v103, v103, v103
	v_fmac_f32_e32 v103, v102, v102
	v_mul_f32_e32 v102, v105, v105
	v_fmac_f32_e32 v102, v104, v104
	v_cvt_pk_bf16_f32 v107, v104, v105
	v_add_f32_e32 v102, v103, v102
	v_mul_f32_e32 v103, v99, v99
	v_mul_f32_e32 v104, v101, v101
	v_fmac_f32_e32 v103, v98, v98
	v_fmac_f32_e32 v104, v100, v100
	v_add_f32_e32 v102, v110, v102
	v_add_f32_e32 v103, v103, v104
	v_add_f32_e32 v104, v102, v103
	ds_bpermute_b32 v105, v213, v104
	v_or_b32_e32 v108, 0x100, v116
	v_mov_b32_e32 v109, v117
	v_lshl_add_u64 v[102:103], s[26:27], 0, v[108:109]
	s_and_saveexec_b64 s[44:45], s[38:39]
	global_store_dwordx2 v[102:103], v[106:107], off
	s_mov_b64 exec, s[44:45]
	global_store_dwordx4 v[194:195], v[98:101], off offset:576
	v_cvt_pk_bf16_f32 v102, v98, v99
	v_or_b32_e32 v116, 0x120, v116
	v_cvt_pk_bf16_f32 v103, v100, v101
	s_waitcnt lgkmcnt(0)
	v_add_f32_e32 v98, v104, v105
	ds_bpermute_b32 v99, v212, v98
	v_lshl_add_u64 v[100:101], s[26:27], 0, v[116:117]
	s_and_saveexec_b64 s[44:45], s[38:39]
	global_store_dwordx2 v[100:101], v[102:103], off
	s_mov_b64 exec, s[44:45]
	s_and_saveexec_b64 s[2:3], vcc
	s_cbranch_execz .LBB0_1529
	s_waitcnt lgkmcnt(0)
	v_add_f32_e32 v98, v98, v99
	ds_write_b32 v128, v98 offset:256
.LBB0_1529:
	s_or_b64 exec, exec, s[2:3]
	s_waitcnt lgkmcnt(0)
	v_lshlrev_b64 v[98:99], 10, v[192:193]
	v_pk_fma_f32 v[96:97], v[96:97], v[114:115], v[160:161]
	v_pk_fma_f32 v[94:95], v[94:95], v[178:179], v[158:159]
	v_lshl_add_u64 v[98:99], v[98:99], 0, v[180:181]
	global_store_dwordx4 v[190:191], v[94:97], off
	v_cvt_pk_bf16_f32 v100, v94, v95
	v_lshlrev_b64 v[98:99], 1, v[98:99]
	v_lshl_add_u64 v[102:103], s[26:27], 0, v[98:99]
	v_mul_f32_e32 v95, v95, v95
	v_fmac_f32_e32 v95, v94, v94
	v_mul_f32_e32 v94, v97, v97
	v_fmac_f32_e32 v94, v96, v96
	v_pk_fma_f32 v[92:93], v[92:93], v[114:115], v[156:157]
	v_pk_fma_f32 v[90:91], v[90:91], v[178:179], v[154:155]
	v_cvt_pk_bf16_f32 v101, v96, v97
	s_and_saveexec_b64 s[44:45], s[38:39]
	global_store_dwordx2 v[102:103], v[100:101], off
	s_mov_b64 exec, s[44:45]
	v_add_f32_e32 v100, v95, v94
	global_store_dwordx4 v[190:191], v[90:93], off offset:64
	v_cvt_pk_bf16_f32 v94, v90, v91
	v_or_b32_e32 v96, 32, v98
	v_mov_b32_e32 v97, v99
	v_mul_f32_e32 v91, v91, v91
	v_fmac_f32_e32 v91, v90, v90
	v_mul_f32_e32 v90, v93, v93
	v_fmac_f32_e32 v90, v92, v92
	v_lshl_add_u64 v[96:97], s[26:27], 0, v[96:97]
	v_add_f32_e32 v90, v91, v90
	v_pk_fma_f32 v[88:89], v[88:89], v[114:115], v[152:153]
	v_pk_fma_f32 v[86:87], v[86:87], v[178:179], v[150:151]
	v_cvt_pk_bf16_f32 v95, v92, v93
	s_and_saveexec_b64 s[44:45], s[38:39]
	global_store_dwordx2 v[96:97], v[94:95], off
	s_mov_b64 exec, s[44:45]
	v_add_f32_e32 v94, v100, v90
	global_store_dwordx4 v[190:191], v[86:89], off offset:512
	v_cvt_pk_bf16_f32 v90, v86, v87
	v_pk_fma_f32 v[84:85], v[84:85], v[114:115], v[148:149]
	v_pk_fma_f32 v[82:83], v[82:83], v[178:179], v[146:147]
	v_mul_f32_e32 v87, v87, v87
	v_fmac_f32_e32 v87, v86, v86
	v_mul_f32_e32 v86, v89, v89
	v_fmac_f32_e32 v86, v88, v88
	v_cvt_pk_bf16_f32 v91, v88, v89
	v_add_f32_e32 v86, v87, v86
	v_mul_f32_e32 v87, v83, v83
	v_mul_f32_e32 v88, v85, v85
	v_fmac_f32_e32 v87, v82, v82
	v_fmac_f32_e32 v88, v84, v84
	v_add_f32_e32 v86, v94, v86
	v_add_f32_e32 v87, v87, v88
	v_add_f32_e32 v88, v86, v87
	ds_bpermute_b32 v89, v213, v88
	v_or_b32_e32 v92, 0x100, v98
	v_mov_b32_e32 v93, v99
	v_lshl_add_u64 v[86:87], s[26:27], 0, v[92:93]
	s_and_saveexec_b64 s[44:45], s[38:39]
	global_store_dwordx2 v[86:87], v[90:91], off
	s_mov_b64 exec, s[44:45]
	global_store_dwordx4 v[190:191], v[82:85], off offset:576
	v_cvt_pk_bf16_f32 v86, v82, v83
	v_or_b32_e32 v98, 0x120, v98
	v_cvt_pk_bf16_f32 v87, v84, v85
	s_waitcnt lgkmcnt(0)
	v_add_f32_e32 v82, v88, v89
	ds_bpermute_b32 v83, v212, v82
	v_lshl_add_u64 v[84:85], s[26:27], 0, v[98:99]
	s_and_saveexec_b64 s[44:45], s[38:39]
	global_store_dwordx2 v[84:85], v[86:87], off
	s_mov_b64 exec, s[44:45]
	s_and_saveexec_b64 s[2:3], vcc
	s_cbranch_execz .LBB0_1531
	s_waitcnt lgkmcnt(0)
	v_add_f32_e32 v82, v82, v83
	ds_write_b32 v128, v82 offset:512
; __device__ __forceinline__ unsigned cvt_pk_bf16(float lo, float hi) { unsigned r; asm volatile("v_cvt_pk_bf16_f32 %0, %1, %2" : "=v"(r) : "v"(lo), "v"(hi)); return r; }
; __device__ __forceinline__ float bperm(float v, int srclane) { return __int_as_float(__builtin_amdgcn_ds_bpermute(srclane << 2, __float_as_int(v))); }
; __device__ __forceinline__ float bperm(float v, int srclane) { return __int_as_float(__builtin_amdgcn_ds_bpermute(srclane << 2, __float_as_int(v))); }
;     __device__ __forceinline__ void fused(f32x4 (&acc)[2][2][4][2], const Unit& u, int wr, int wc, int fr, int fq, PG8_LAS unsigned char* lds, int wid, int lane) const {
;     ...
;         for (int ai = 0; ai < 2; ++ai) { f32x4 xv[4][2][2];
; #pragma unroll
;             for (int m = 0; m < 4; ++m)
; #pragma unroll
;                 for (int bj = 0; bj < 2; ++bj)
; #pragma unroll
;                     for (int n = 0; n < 2; ++n) xv[m][bj][n] = *(const f32x4*)(xin + (size_t)(row0 + ai * HALF + m * 16) * 1024 + col0 + bj * HALF + n * 16);
;             __builtin_amdgcn_sched_barrier(0);
; #pragma unroll
;             for (int m = 0; m < 4; ++m) { const int row = row0 + ai * HALF + m * 16; float q = 0.f;
; #pragma unroll
;                 for (int bj = 0; bj < 2; ++bj)
; #pragma unroll
;                     for (int n = 0; n < 2; ++n) { const size_t off = (size_t)row * 1024 + col0 + bj * HALF + n * 16;
;                         f32x4 v = xv[m][bj][n] + acc[ai][bj][m][n] * scl; *(f32x4*)(x + off) = v;
;                         u32x2 w; w.x = cvt_pk_bf16(v[0], v[1]); w.y = cvt_pk_bf16(v[2], v[3]); *(u32x2*)(xb + off) = w;
;                         q += (v[0] * v[0] + v[1] * v[1]) + (v[2] * v[2] + v[3] * v[3]); }
;                 q += bperm(q, (fr + 16 * fq) ^ 16); q += bperm(q, (fr + 16 * fq) ^ 32);
;                 if (fq == 0) P[(ai * HALF + wr * 64 + m * 16 + fr) * 4 + wc] = q; }
.LBB0_1531:
	s_or_b64 exec, exec, s[2:3]
	v_mov_b32_e32 v124, v178
	v_mov_b32_e32 v125, v178
	s_waitcnt lgkmcnt(0)
	v_lshlrev_b64 v[82:83], 10, v[188:189]
	v_pk_fma_f32 v[80:81], v[80:81], v[124:125], v[144:145]
	v_pk_fma_f32 v[78:79], v[78:79], v[178:179], v[142:143]
	v_lshl_add_u64 v[82:83], v[82:83], 0, v[180:181]
	global_store_dwordx4 v[186:187], v[78:81], off
	v_cvt_pk_bf16_f32 v84, v78, v79
	v_lshlrev_b64 v[82:83], 1, v[82:83]
	v_lshl_add_u64 v[86:87], s[26:27], 0, v[82:83]
	v_mul_f32_e32 v79, v79, v79
	v_fmac_f32_e32 v79, v78, v78
	v_mul_f32_e32 v78, v81, v81
	v_fmac_f32_e32 v78, v80, v80
	v_pk_fma_f32 v[76:77], v[76:77], v[124:125], v[140:141]
	v_pk_fma_f32 v[74:75], v[74:75], v[178:179], v[138:139]
	v_cvt_pk_bf16_f32 v85, v80, v81
	s_and_saveexec_b64 s[44:45], s[38:39]
	global_store_dwordx2 v[86:87], v[84:85], off
	s_mov_b64 exec, s[44:45]
	v_add_f32_e32 v84, v79, v78
	global_store_dwordx4 v[186:187], v[74:77], off offset:64
	v_cvt_pk_bf16_f32 v78, v74, v75
	v_or_b32_e32 v80, 32, v82
	v_mov_b32_e32 v81, v83
	v_mul_f32_e32 v75, v75, v75
	v_fmac_f32_e32 v75, v74, v74
	v_mul_f32_e32 v74, v77, v77
	v_fmac_f32_e32 v74, v76, v76
	v_lshl_add_u64 v[80:81], s[26:27], 0, v[80:81]
	v_add_f32_e32 v74, v75, v74
	v_pk_fma_f32 v[72:73], v[72:73], v[124:125], v[136:137]
	v_pk_fma_f32 v[70:71], v[70:71], v[178:179], v[134:135]
	v_cvt_pk_bf16_f32 v79, v76, v77
	s_and_saveexec_b64 s[44:45], s[38:39]
	global_store_dwordx2 v[80:81], v[78:79], off
	s_mov_b64 exec, s[44:45]
	v_add_f32_e32 v78, v84, v74
	global_store_dwordx4 v[186:187], v[70:73], off offset:512
	v_cvt_pk_bf16_f32 v74, v70, v71
	v_pk_fma_f32 v[68:69], v[68:69], v[124:125], v[132:133]
	v_pk_fma_f32 v[66:67], v[66:67], v[178:179], v[130:131]
	v_mul_f32_e32 v71, v71, v71
	v_fmac_f32_e32 v71, v70, v70
	v_mul_f32_e32 v70, v73, v73
	v_fmac_f32_e32 v70, v72, v72
	v_cvt_pk_bf16_f32 v75, v72, v73
	v_add_f32_e32 v70, v71, v70
	v_mul_f32_e32 v71, v67, v67
	v_mul_f32_e32 v72, v69, v69
	v_fmac_f32_e32 v71, v66, v66
	v_fmac_f32_e32 v72, v68, v68
	v_add_f32_e32 v70, v78, v70
	v_add_f32_e32 v71, v71, v72
	v_add_f32_e32 v72, v70, v71
	ds_bpermute_b32 v73, v213, v72
	v_or_b32_e32 v76, 0x100, v82
	v_mov_b32_e32 v77, v83
	v_lshl_add_u64 v[70:71], s[26:27], 0, v[76:77]
	s_and_saveexec_b64 s[44:45], s[38:39]
	global_store_dwordx2 v[70:71], v[74:75], off
	s_mov_b64 exec, s[44:45]
	global_store_dwordx4 v[186:187], v[66:69], off offset:576
	v_cvt_pk_bf16_f32 v70, v66, v67
	v_or_b32_e32 v82, 0x120, v82
	v_cvt_pk_bf16_f32 v71, v68, v69
	s_waitcnt lgkmcnt(0)
	v_add_f32_e32 v66, v72, v73
	ds_bpermute_b32 v67, v212, v66
	v_lshl_add_u64 v[68:69], s[26:27], 0, v[82:83]
	s_and_saveexec_b64 s[44:45], s[38:39]
	global_store_dwordx2 v[68:69], v[70:71], off
	s_mov_b64 exec, s[44:45]
	s_and_saveexec_b64 s[2:3], vcc
	s_cbranch_execz .LBB0_1533
	s_waitcnt lgkmcnt(0)
	v_add_f32_e32 v66, v66, v67
	ds_write_b32 v128, v66 offset:768
.LBB0_1533:
	s_or_b64 exec, exec, s[2:3]
	v_add_u32_e32 v146, 0x80, v182
	v_ashrrev_i32_e32 v147, 31, v146
	v_add_u32_e32 v126, 0x90, v182
	s_waitcnt lgkmcnt(0)
	v_lshlrev_b64 v[66:67], 12, v[146:147]
	v_ashrrev_i32_e32 v127, 31, v126
	v_add_u32_e32 v120, 0xa0, v182
	v_lshl_add_u64 v[148:149], v[184:185], 0, v[66:67]
	v_lshlrev_b64 v[66:67], 12, v[126:127]
	v_ashrrev_i32_e32 v121, 31, v120
	v_add_u32_e32 v116, 0xb0, v182
	v_lshl_add_u64 v[122:123], v[184:185], 0, v[66:67]
	v_lshlrev_b64 v[66:67], 12, v[120:121]
	v_ashrrev_i32_e32 v117, 31, v116
	v_lshl_add_u64 v[118:119], v[184:185], 0, v[66:67]
	v_lshlrev_b64 v[66:67], 12, v[116:117]
	v_lshl_add_u64 v[114:115], v[184:185], 0, v[66:67]
	global_load_dwordx4 v[130:133], v[148:149], off
	global_load_dwordx4 v[134:137], v[148:149], off offset:64
	global_load_dwordx4 v[138:141], v[148:149], off offset:512
	global_load_dwordx4 v[142:145], v[148:149], off offset:576
	global_load_dwordx4 v[110:113], v[122:123], off
	global_load_dwordx4 v[106:109], v[122:123], off offset:64
	global_load_dwordx4 v[102:105], v[122:123], off offset:512
	global_load_dwordx4 v[98:101], v[122:123], off offset:576
	global_load_dwordx4 v[94:97], v[118:119], off
	global_load_dwordx4 v[90:93], v[118:119], off offset:64
	global_load_dwordx4 v[86:89], v[118:119], off offset:512
	global_load_dwordx4 v[82:85], v[118:119], off offset:576
	global_load_dwordx4 v[78:81], v[114:115], off
	global_load_dwordx4 v[74:77], v[114:115], off offset:64
	global_load_dwordx4 v[70:73], v[114:115], off offset:512
	global_load_dwordx4 v[66:69], v[114:115], off offset:576
	v_lshlrev_b64 v[146:147], 10, v[146:147]
	s_waitcnt vmcnt(15)
	v_pk_fma_f32 v[62:63], v[62:63], v[124:125], v[132:133]
	v_pk_fma_f32 v[60:61], v[60:61], v[178:179], v[130:131]
	v_lshl_add_u64 v[146:147], v[146:147], 0, v[180:181]
	global_store_dwordx4 v[148:149], v[60:63], off
	v_cvt_pk_bf16_f32 v130, v60, v61
	v_lshlrev_b64 v[132:133], 1, v[146:147]
	v_lshl_add_u64 v[146:147], s[26:27], 0, v[132:133]
	v_mul_f32_e32 v61, v61, v61
	v_fmac_f32_e32 v61, v60, v60
	v_mul_f32_e32 v60, v63, v63
	v_fmac_f32_e32 v60, v62, v62
	s_waitcnt vmcnt(15)
	v_pk_fma_f32 v[58:59], v[58:59], v[124:125], v[136:137]
	v_pk_fma_f32 v[56:57], v[56:57], v[178:179], v[134:135]
	v_cvt_pk_bf16_f32 v131, v62, v63
	s_and_saveexec_b64 s[44:45], s[38:39]
	global_store_dwordx2 v[146:147], v[130:131], off
	s_mov_b64 exec, s[44:45]
	v_add_f32_e32 v129, v61, v60
	global_store_dwordx4 v[148:149], v[56:59], off offset:64
	v_cvt_pk_bf16_f32 v60, v56, v57
	v_or_b32_e32 v62, 32, v132
	v_mov_b32_e32 v63, v133
	v_mul_f32_e32 v57, v57, v57
	v_fmac_f32_e32 v57, v56, v56
	v_mul_f32_e32 v56, v59, v59
	v_fmac_f32_e32 v56, v58, v58
	v_lshl_add_u64 v[62:63], s[26:27], 0, v[62:63]
	v_add_f32_e32 v56, v57, v56
	s_waitcnt vmcnt(16)
; __device__ __forceinline__ unsigned cvt_pk_bf16(float lo, float hi) { unsigned r; asm volatile("v_cvt_pk_bf16_f32 %0, %1, %2" : "=v"(r) : "v"(lo), "v"(hi)); return r; }
; __device__ __forceinline__ float bperm(float v, int srclane) { return __int_as_float(__builtin_amdgcn_ds_bpermute(srclane << 2, __float_as_int(v))); }
; __device__ __forceinline__ float bperm(float v, int srclane) { return __int_as_float(__builtin_amdgcn_ds_bpermute(srclane << 2, __float_as_int(v))); }
;     __device__ __forceinline__ void fused(f32x4 (&acc)[2][2][4][2], const Unit& u, int wr, int wc, int fr, int fq, PG8_LAS unsigned char* lds, int wid, int lane) const {
;     ...
;         for (int ai = 0; ai < 2; ++ai) { f32x4 xv[4][2][2];
; #pragma unroll
;             for (int m = 0; m < 4; ++m)
; #pragma unroll
;                 for (int bj = 0; bj < 2; ++bj)
; #pragma unroll
;                     for (int n = 0; n < 2; ++n) xv[m][bj][n] = *(const f32x4*)(xin + (size_t)(row0 + ai * HALF + m * 16) * 1024 + col0 + bj * HALF + n * 16);
;             __builtin_amdgcn_sched_barrier(0);
; #pragma unroll
;             for (int m = 0; m < 4; ++m) { const int row = row0 + ai * HALF + m * 16; float q = 0.f;
; #pragma unroll
;                 for (int bj = 0; bj < 2; ++bj)
; #pragma unroll
;                     for (int n = 0; n < 2; ++n) { const size_t off = (size_t)row * 1024 + col0 + bj * HALF + n * 16;
;                         f32x4 v = xv[m][bj][n] + acc[ai][bj][m][n] * scl; *(f32x4*)(x + off) = v;
;                         u32x2 w; w.x = cvt_pk_bf16(v[0], v[1]); w.y = cvt_pk_bf16(v[2], v[3]); *(u32x2*)(xb + off) = w;
;                         q += (v[0] * v[0] + v[1] * v[1]) + (v[2] * v[2] + v[3] * v[3]); }
;                 q += bperm(q, (fr + 16 * fq) ^ 16); q += bperm(q, (fr + 16 * fq) ^ 32);
;                 if (fq == 0) P[(ai * HALF + wr * 64 + m * 16 + fr) * 4 + wc] = q; }
	v_pk_fma_f32 v[54:55], v[54:55], v[124:125], v[140:141]
	v_pk_fma_f32 v[52:53], v[52:53], v[178:179], v[138:139]
	v_cvt_pk_bf16_f32 v61, v58, v59
	s_and_saveexec_b64 s[44:45], s[38:39]
	global_store_dwordx2 v[62:63], v[60:61], off
	s_mov_b64 exec, s[44:45]
	v_add_f32_e32 v60, v129, v56
	global_store_dwordx4 v[148:149], v[52:55], off offset:512
	v_cvt_pk_bf16_f32 v56, v52, v53
	s_waitcnt vmcnt(17)
	v_pk_fma_f32 v[50:51], v[50:51], v[124:125], v[144:145]
	v_pk_fma_f32 v[48:49], v[48:49], v[178:179], v[142:143]
	v_mul_f32_e32 v53, v53, v53
	v_fmac_f32_e32 v53, v52, v52
	v_mul_f32_e32 v52, v55, v55
	v_fmac_f32_e32 v52, v54, v54
	v_cvt_pk_bf16_f32 v57, v54, v55
	v_add_f32_e32 v52, v53, v52
	v_mul_f32_e32 v53, v49, v49
	v_mul_f32_e32 v54, v51, v51
	v_fmac_f32_e32 v53, v48, v48
	v_fmac_f32_e32 v54, v50, v50
	v_add_f32_e32 v52, v60, v52
	v_add_f32_e32 v53, v53, v54
	v_add_f32_e32 v54, v52, v53
	ds_bpermute_b32 v55, v213, v54
	v_or_b32_e32 v58, 0x100, v132
	v_mov_b32_e32 v59, v133
	v_lshl_add_u64 v[52:53], s[26:27], 0, v[58:59]
	s_and_saveexec_b64 s[44:45], s[38:39]
	global_store_dwordx2 v[52:53], v[56:57], off
	s_mov_b64 exec, s[44:45]
	global_store_dwordx4 v[148:149], v[48:51], off offset:576
	v_cvt_pk_bf16_f32 v52, v48, v49
	v_or_b32_e32 v132, 0x120, v132
	v_cvt_pk_bf16_f32 v53, v50, v51
	s_waitcnt lgkmcnt(0)
	v_add_f32_e32 v48, v54, v55
	ds_bpermute_b32 v49, v212, v48
	v_lshl_add_u64 v[50:51], s[26:27], 0, v[132:133]
	s_and_saveexec_b64 s[44:45], s[38:39]
	global_store_dwordx2 v[50:51], v[52:53], off
	s_mov_b64 exec, s[44:45]
	s_and_saveexec_b64 s[2:3], vcc
	s_cbranch_execz .LBB0_1535
	s_waitcnt lgkmcnt(0)
	v_add_f32_e32 v48, v48, v49
	ds_write_b32 v128, v48 offset:2048
.LBB0_1535:
	s_or_b64 exec, exec, s[2:3]
	s_waitcnt lgkmcnt(0)
	v_lshlrev_b64 v[48:49], 10, v[126:127]
	v_lshl_add_u64 v[50:51], v[48:49], 0, v[180:181]
	v_mov_b32_e32 v48, v178
	v_mov_b32_e32 v49, v178
	s_waitcnt vmcnt(19)
	v_pk_fma_f32 v[46:47], v[46:47], v[48:49], v[112:113]
	v_pk_fma_f32 v[44:45], v[44:45], v[178:179], v[110:111]
	global_store_dwordx4 v[122:123], v[44:47], off
	v_cvt_pk_bf16_f32 v52, v44, v45
	v_lshlrev_b64 v[50:51], 1, v[50:51]
	v_lshl_add_u64 v[54:55], s[26:27], 0, v[50:51]
	v_mul_f32_e32 v45, v45, v45
	v_fmac_f32_e32 v45, v44, v44
	v_mul_f32_e32 v44, v47, v47
	v_fmac_f32_e32 v44, v46, v46
	s_waitcnt vmcnt(19)
	v_pk_fma_f32 v[42:43], v[42:43], v[48:49], v[108:109]
	v_pk_fma_f32 v[40:41], v[40:41], v[178:179], v[106:107]
	v_cvt_pk_bf16_f32 v53, v46, v47
	s_and_saveexec_b64 s[44:45], s[38:39]
	global_store_dwordx2 v[54:55], v[52:53], off
	s_mov_b64 exec, s[44:45]
	v_add_f32_e32 v52, v45, v44
	global_store_dwordx4 v[122:123], v[40:43], off offset:64
	v_cvt_pk_bf16_f32 v44, v40, v41
	v_or_b32_e32 v46, 32, v50
	v_mov_b32_e32 v47, v51
	v_mul_f32_e32 v41, v41, v41
	v_fmac_f32_e32 v41, v40, v40
	v_mul_f32_e32 v40, v43, v43
	v_fmac_f32_e32 v40, v42, v42
	v_lshl_add_u64 v[46:47], s[26:27], 0, v[46:47]
	v_add_f32_e32 v40, v41, v40
	s_waitcnt vmcnt(20)
	v_pk_fma_f32 v[38:39], v[38:39], v[48:49], v[104:105]
	v_pk_fma_f32 v[36:37], v[36:37], v[178:179], v[102:103]
	v_cvt_pk_bf16_f32 v45, v42, v43
	s_and_saveexec_b64 s[44:45], s[38:39]
	global_store_dwordx2 v[46:47], v[44:45], off
	s_mov_b64 exec, s[44:45]
	v_add_f32_e32 v44, v52, v40
	global_store_dwordx4 v[122:123], v[36:39], off offset:512
	v_cvt_pk_bf16_f32 v40, v36, v37
	s_waitcnt vmcnt(21)
	v_pk_fma_f32 v[34:35], v[34:35], v[48:49], v[100:101]
	v_pk_fma_f32 v[32:33], v[32:33], v[178:179], v[98:99]
	v_mul_f32_e32 v37, v37, v37
	v_fmac_f32_e32 v37, v36, v36
	v_mul_f32_e32 v36, v39, v39
	v_fmac_f32_e32 v36, v38, v38
	v_cvt_pk_bf16_f32 v41, v38, v39
	v_add_f32_e32 v36, v37, v36
	v_mul_f32_e32 v37, v33, v33
	v_mul_f32_e32 v38, v35, v35
	v_fmac_f32_e32 v37, v32, v32
	v_fmac_f32_e32 v38, v34, v34
	v_add_f32_e32 v36, v44, v36
	v_add_f32_e32 v37, v37, v38
	v_add_f32_e32 v38, v36, v37
	ds_bpermute_b32 v39, v213, v38
	v_or_b32_e32 v42, 0x100, v50
	v_mov_b32_e32 v43, v51
	v_lshl_add_u64 v[36:37], s[26:27], 0, v[42:43]
	s_and_saveexec_b64 s[44:45], s[38:39]
	global_store_dwordx2 v[36:37], v[40:41], off
	s_mov_b64 exec, s[44:45]
	global_store_dwordx4 v[122:123], v[32:35], off offset:576
	v_cvt_pk_bf16_f32 v36, v32, v33
	v_or_b32_e32 v50, 0x120, v50
	v_cvt_pk_bf16_f32 v37, v34, v35
	s_waitcnt lgkmcnt(0)
	v_add_f32_e32 v32, v38, v39
	ds_bpermute_b32 v33, v212, v32
	v_lshl_add_u64 v[34:35], s[26:27], 0, v[50:51]
	s_and_saveexec_b64 s[44:45], s[38:39]
	global_store_dwordx2 v[34:35], v[36:37], off
	s_mov_b64 exec, s[44:45]
	s_and_saveexec_b64 s[2:3], vcc
	s_cbranch_execz .LBB0_1537
	s_waitcnt lgkmcnt(0)
	v_add_f32_e32 v32, v32, v33
	ds_write_b32 v128, v32 offset:2304
; __device__ __forceinline__ unsigned cvt_pk_bf16(float lo, float hi) { unsigned r; asm volatile("v_cvt_pk_bf16_f32 %0, %1, %2" : "=v"(r) : "v"(lo), "v"(hi)); return r; }
; __device__ __forceinline__ float bperm(float v, int srclane) { return __int_as_float(__builtin_amdgcn_ds_bpermute(srclane << 2, __float_as_int(v))); }
; __device__ __forceinline__ float bperm(float v, int srclane) { return __int_as_float(__builtin_amdgcn_ds_bpermute(srclane << 2, __float_as_int(v))); }
;     __device__ __forceinline__ void fused(f32x4 (&acc)[2][2][4][2], const Unit& u, int wr, int wc, int fr, int fq, PG8_LAS unsigned char* lds, int wid, int lane) const {
;     ...
;         for (int ai = 0; ai < 2; ++ai) { f32x4 xv[4][2][2];
; #pragma unroll
;             for (int m = 0; m < 4; ++m)
; #pragma unroll
;                 for (int bj = 0; bj < 2; ++bj)
; #pragma unroll
;                     for (int n = 0; n < 2; ++n) xv[m][bj][n] = *(const f32x4*)(xin + (size_t)(row0 + ai * HALF + m * 16) * 1024 + col0 + bj * HALF + n * 16);
;             __builtin_amdgcn_sched_barrier(0);
; #pragma unroll
;             for (int m = 0; m < 4; ++m) { const int row = row0 + ai * HALF + m * 16; float q = 0.f;
; #pragma unroll
;                 for (int bj = 0; bj < 2; ++bj)
; #pragma unroll
;                     for (int n = 0; n < 2; ++n) { const size_t off = (size_t)row * 1024 + col0 + bj * HALF + n * 16;
;                         f32x4 v = xv[m][bj][n] + acc[ai][bj][m][n] * scl; *(f32x4*)(x + off) = v;
;                         u32x2 w; w.x = cvt_pk_bf16(v[0], v[1]); w.y = cvt_pk_bf16(v[2], v[3]); *(u32x2*)(xb + off) = w;
;                         q += (v[0] * v[0] + v[1] * v[1]) + (v[2] * v[2] + v[3] * v[3]); }
;                 q += bperm(q, (fr + 16 * fq) ^ 16); q += bperm(q, (fr + 16 * fq) ^ 32);
;                 if (fq == 0) P[(ai * HALF + wr * 64 + m * 16 + fr) * 4 + wc] = q; }
.LBB0_1537:
	s_or_b64 exec, exec, s[2:3]
	s_waitcnt lgkmcnt(0)
	v_lshlrev_b64 v[32:33], 10, v[120:121]
	s_waitcnt vmcnt(23)
	v_pk_fma_f32 v[30:31], v[30:31], v[48:49], v[96:97]
	v_pk_fma_f32 v[28:29], v[28:29], v[178:179], v[94:95]
	v_lshl_add_u64 v[32:33], v[32:33], 0, v[180:181]
	global_store_dwordx4 v[118:119], v[28:31], off
	v_cvt_pk_bf16_f32 v34, v28, v29
	v_lshlrev_b64 v[32:33], 1, v[32:33]
	v_lshl_add_u64 v[36:37], s[26:27], 0, v[32:33]
	v_mul_f32_e32 v29, v29, v29
	v_fmac_f32_e32 v29, v28, v28
	v_mul_f32_e32 v28, v31, v31
	v_fmac_f32_e32 v28, v30, v30
	s_waitcnt vmcnt(23)
	v_pk_fma_f32 v[26:27], v[26:27], v[48:49], v[92:93]
	v_pk_fma_f32 v[24:25], v[24:25], v[178:179], v[90:91]
	v_cvt_pk_bf16_f32 v35, v30, v31
	s_and_saveexec_b64 s[44:45], s[38:39]
	global_store_dwordx2 v[36:37], v[34:35], off
	s_mov_b64 exec, s[44:45]
	v_add_f32_e32 v34, v29, v28
	global_store_dwordx4 v[118:119], v[24:27], off offset:64
	v_cvt_pk_bf16_f32 v28, v24, v25
	v_or_b32_e32 v30, 32, v32
	v_mov_b32_e32 v31, v33
	v_mul_f32_e32 v25, v25, v25
	v_fmac_f32_e32 v25, v24, v24
	v_mul_f32_e32 v24, v27, v27
	v_fmac_f32_e32 v24, v26, v26
	v_lshl_add_u64 v[30:31], s[26:27], 0, v[30:31]
	v_add_f32_e32 v24, v25, v24
	s_waitcnt vmcnt(24)
	v_pk_fma_f32 v[22:23], v[22:23], v[48:49], v[88:89]
	v_pk_fma_f32 v[20:21], v[20:21], v[178:179], v[86:87]
	v_cvt_pk_bf16_f32 v29, v26, v27
	s_and_saveexec_b64 s[44:45], s[38:39]
	global_store_dwordx2 v[30:31], v[28:29], off
	s_mov_b64 exec, s[44:45]
	v_add_f32_e32 v28, v34, v24
	global_store_dwordx4 v[118:119], v[20:23], off offset:512
	v_cvt_pk_bf16_f32 v24, v20, v21
	s_waitcnt vmcnt(25)
	v_pk_fma_f32 v[18:19], v[18:19], v[48:49], v[84:85]
	v_pk_fma_f32 v[16:17], v[16:17], v[178:179], v[82:83]
	v_mul_f32_e32 v21, v21, v21
	v_fmac_f32_e32 v21, v20, v20
	v_mul_f32_e32 v20, v23, v23
	v_fmac_f32_e32 v20, v22, v22
	v_cvt_pk_bf16_f32 v25, v22, v23
	v_add_f32_e32 v20, v21, v20
	v_mul_f32_e32 v21, v17, v17
	v_mul_f32_e32 v22, v19, v19
	v_fmac_f32_e32 v21, v16, v16
	v_fmac_f32_e32 v22, v18, v18
	v_add_f32_e32 v20, v28, v20
	v_add_f32_e32 v21, v21, v22
	v_add_f32_e32 v22, v20, v21
	ds_bpermute_b32 v23, v213, v22
	v_or_b32_e32 v26, 0x100, v32
	v_mov_b32_e32 v27, v33
	v_lshl_add_u64 v[20:21], s[26:27], 0, v[26:27]
	s_and_saveexec_b64 s[44:45], s[38:39]
	global_store_dwordx2 v[20:21], v[24:25], off
	s_mov_b64 exec, s[44:45]
	global_store_dwordx4 v[118:119], v[16:19], off offset:576
	v_cvt_pk_bf16_f32 v20, v16, v17
	v_or_b32_e32 v32, 0x120, v32
	v_cvt_pk_bf16_f32 v21, v18, v19
	s_waitcnt lgkmcnt(0)
	v_add_f32_e32 v16, v22, v23
	ds_bpermute_b32 v17, v212, v16
	v_lshl_add_u64 v[18:19], s[26:27], 0, v[32:33]
	s_and_saveexec_b64 s[44:45], s[38:39]
	global_store_dwordx2 v[18:19], v[20:21], off
	s_mov_b64 exec, s[44:45]
	s_and_saveexec_b64 s[2:3], vcc
	s_cbranch_execz .LBB0_1539
	s_waitcnt lgkmcnt(0)
	v_add_f32_e32 v16, v16, v17
	ds_write_b32 v128, v16 offset:2560
.LBB0_1539:
	s_or_b64 exec, exec, s[2:3]
	v_mov_b32_e32 v18, v178
	v_mov_b32_e32 v19, v178
	s_waitcnt lgkmcnt(0)
	v_lshlrev_b64 v[16:17], 10, v[116:117]
	s_waitcnt vmcnt(27)
	v_pk_fma_f32 v[14:15], v[14:15], v[18:19], v[80:81]
	v_pk_fma_f32 v[12:13], v[12:13], v[178:179], v[78:79]
	v_lshl_add_u64 v[16:17], v[16:17], 0, v[180:181]
	global_store_dwordx4 v[114:115], v[12:15], off
	v_cvt_pk_bf16_f32 v20, v12, v13
	v_lshlrev_b64 v[16:17], 1, v[16:17]
	v_lshl_add_u64 v[22:23], s[26:27], 0, v[16:17]
	v_mul_f32_e32 v13, v13, v13
	v_fmac_f32_e32 v13, v12, v12
	v_mul_f32_e32 v12, v15, v15
	v_fmac_f32_e32 v12, v14, v14
	s_waitcnt vmcnt(27)
	v_pk_fma_f32 v[10:11], v[10:11], v[18:19], v[76:77]
	v_pk_fma_f32 v[8:9], v[8:9], v[178:179], v[74:75]
	v_cvt_pk_bf16_f32 v21, v14, v15
	s_and_saveexec_b64 s[44:45], s[38:39]
	global_store_dwordx2 v[22:23], v[20:21], off
	s_mov_b64 exec, s[44:45]
	v_add_f32_e32 v20, v13, v12
	global_store_dwordx4 v[114:115], v[8:11], off offset:64
	v_cvt_pk_bf16_f32 v12, v8, v9
	v_or_b32_e32 v14, 32, v16
	v_mov_b32_e32 v15, v17
	v_mul_f32_e32 v9, v9, v9
	v_fmac_f32_e32 v9, v8, v8
	v_mul_f32_e32 v8, v11, v11
	v_fmac_f32_e32 v8, v10, v10
	v_lshl_add_u64 v[14:15], s[26:27], 0, v[14:15]
	v_add_f32_e32 v8, v9, v8
	s_waitcnt vmcnt(28)
	v_pk_fma_f32 v[6:7], v[6:7], v[18:19], v[72:73]
	v_pk_fma_f32 v[4:5], v[4:5], v[178:179], v[70:71]
	v_cvt_pk_bf16_f32 v13, v10, v11
	s_and_saveexec_b64 s[44:45], s[38:39]
	global_store_dwordx2 v[14:15], v[12:13], off
	s_mov_b64 exec, s[44:45]
	v_add_f32_e32 v12, v20, v8
	global_store_dwordx4 v[114:115], v[4:7], off offset:512
	v_cvt_pk_bf16_f32 v8, v4, v5
	s_waitcnt vmcnt(29)
	v_pk_fma_f32 v[2:3], v[2:3], v[18:19], v[68:69]
	v_pk_fma_f32 v[0:1], v[0:1], v[178:179], v[66:67]
	v_mul_f32_e32 v5, v5, v5
	v_fmac_f32_e32 v5, v4, v4
	v_mul_f32_e32 v4, v7, v7
	v_fmac_f32_e32 v4, v6, v6
	v_cvt_pk_bf16_f32 v9, v6, v7
	v_add_f32_e32 v4, v5, v4
	v_mul_f32_e32 v5, v1, v1
	v_mul_f32_e32 v6, v3, v3
	v_fmac_f32_e32 v5, v0, v0
	v_fmac_f32_e32 v6, v2, v2
	v_add_f32_e32 v4, v12, v4
	v_add_f32_e32 v5, v5, v6
	v_add_f32_e32 v6, v4, v5
	ds_bpermute_b32 v7, v213, v6
	v_or_b32_e32 v10, 0x100, v16
	v_mov_b32_e32 v11, v17
	v_lshl_add_u64 v[4:5], s[26:27], 0, v[10:11]
	s_and_saveexec_b64 s[44:45], s[38:39]
	global_store_dwordx2 v[4:5], v[8:9], off
	s_mov_b64 exec, s[44:45]
	global_store_dwordx4 v[114:115], v[0:3], off offset:576
	v_cvt_pk_bf16_f32 v4, v0, v1
	v_or_b32_e32 v16, 0x120, v16
	v_cvt_pk_bf16_f32 v5, v2, v3
	s_waitcnt lgkmcnt(0)
	v_add_f32_e32 v0, v6, v7
	ds_bpermute_b32 v1, v212, v0
	v_lshl_add_u64 v[2:3], s[26:27], 0, v[16:17]
	s_and_saveexec_b64 s[44:45], s[38:39]
	global_store_dwordx2 v[2:3], v[4:5], off
	s_mov_b64 exec, s[44:45]
	s_and_saveexec_b64 s[2:3], vcc
	s_cbranch_execz .LBB0_1541
	s_waitcnt lgkmcnt(0)
	v_add_f32_e32 v0, v0, v1
	ds_write_b32 v128, v0 offset:2816
